# deferred P3->P4a panel wait: poll+acquire moved to the epilogue of P4a sub-unit 1 (only sub-unit 3 reads the P3 output); on top of barrier invalidate hoists
# speedup vs baseline: 1.0027x; 1.0027x over previous
.LBB0_898:
	s_mov_b64 s[2:3], s[74:75]
	s_waitcnt vmcnt(0)
	s_barrier
	s_getreg_b32 s0, hwreg(HW_REG_HW_ID, 0, 6)
	s_lshl_b32 s0, s0, 2
	s_and_b32 s0, s0, 0xfc
	s_add_i32 s0, s0, 0
	s_add_i32 s0, s0, 0x20200
	v_mov_b32_e32 v0, s0
	ds_read_b32 v0, v0
	v_readlane_b32 s0, v253, 12
	v_readlane_b32 s1, v253, 13
	s_add_i32 s0, s68, s0
	v_mbcnt_lo_u32_b32 v1, -1, 0
	v_mbcnt_hi_u32_b32 v1, -1, v1
	s_waitcnt lgkmcnt(0)
	v_readfirstlane_b32 s4, v0
	s_lshl_b32 s4, s4, 6
	v_sub_u32_e32 v0, 0, v1
	s_ashr_i32 s1, s0, 31
	s_load_dwordx2 s[100:101], s[74:75], 0xf8
	s_lshl_b64 vcc, s[0:1], 2
	s_waitcnt lgkmcnt(0)
	s_add_u32 s100, s100, vcc_lo
	s_addc_u32 s101, s101, vcc_hi
	s_add_u32 s100, s100, 0xb400
	s_addc_u32 s101, s101, 0
	v_cmp_eq_u32_e32 vcc, s4, v0
	s_and_saveexec_b64 s[4:5], vcc
	s_cbranch_execz .LBB0_901
	s_mov_b64 s[8:9], exec
	v_mbcnt_lo_u32_b32 v0, s8, 0
	v_mbcnt_hi_u32_b32 v0, s9, v0
	v_cmp_eq_u32_e32 vcc, 0, v0
	s_and_b64 s[10:11], exec, vcc
	s_mov_b64 exec, s[10:11]
	s_cbranch_execz .LBB0_901
	s_load_dwordx2 s[2:3], s[2:3], 0xf8
	s_lshl_b64 s[10:11], s[0:1], 2
	v_mov_b32_e32 v1, 0xb000
	s_waitcnt lgkmcnt(0)
	s_add_u32 s2, s2, s10
	s_addc_u32 s3, s3, s11
	s_bcnt1_i32_b64 s8, s[8:9]
	v_mov_b32_e32 v0, s8
	global_atomic_add v1, v0, s[2:3] offset:1024
.LBB0_901:
	s_or_b64 exec, exec, s[4:5]
	s_mov_b64 s[4:5], s[74:75]
	s_getreg_b32 s2, hwreg(HW_REG_HW_ID, 0, 6)
	s_lshl_b32 s2, s2, 2
	s_and_b32 s2, s2, 0xfc
	s_add_i32 s2, s2, 0
	s_add_i32 s2, s2, 0x20200
	v_mov_b32_e32 v0, s2
	ds_read_b32 v0, v0
	v_mbcnt_lo_u32_b32 v1, -1, 0
	v_mbcnt_hi_u32_b32 v1, -1, v1
	s_waitcnt lgkmcnt(0)
	v_readfirstlane_b32 s2, v0
	s_lshl_b32 s2, s2, 6
	v_sub_u32_e32 v0, 0, v1
	v_cmp_eq_u32_e32 vcc, s2, v0
	s_and_saveexec_b64 s[2:3], vcc
	s_branch .LBB0_914

.LBB0_924:
	s_cmp_lg_u32 s43, 1
	s_cbranch_scc1 .Lmy_pw1_a
	s_cmp_lg_u32 s30, 0
	s_cbranch_scc1 .Lmy_pw1_a
	global_load_dword v174, v137, s[100:101] sc1
.Lmy_pw1_a:
	v_mov_b32_e32 v136, v194
	v_mov_b32_e32 v138, v193
	s_lshl_b32 s8, s47, 8
	s_and_b32 s8, s8, 0x1f00
	s_add_i32 s8, s8, s31
	v_add_u32_e32 v172, s8, v138
	s_lshl_b32 s8, s46, 7
	s_and_b32 s8, s8, 0x380
	s_ashr_i32 s15, s46, 3
	s_or_b32 s8, s8, s34
	s_waitcnt vmcnt(0)
	s_cmp_lg_u32 s43, 1
	s_cbranch_scc1 .Lmy_pw1_done
	s_cmp_lg_u32 s30, 0
	s_cbranch_scc1 .Lmy_pw1_done
.Lmy_pw1_chk:
	v_cmp_lt_u32_e32 vcc, 7, v174
	s_cbranch_vccnz .Lmy_pw1_ok
	s_sleep 1
	global_load_dword v174, v137, s[100:101] sc1
	s_waitcnt vmcnt(0)
	s_branch .Lmy_pw1_chk

.Lmy_pw1_done:
	v_lshlrev_b32_e32 v138, 16, v1
	v_and_b32_e32 v139, 0xffff0000, v1
	s_cmp_lt_u32 s46, 8
	v_pk_mul_f32 v[178:179], v[94:95], v[138:139]
	v_pk_fma_f32 v[94:95], v[94:95], v[138:139], v[170:171]
	v_lshlrev_b32_e32 v138, 16, v0
	v_and_b32_e32 v139, 0xffff0000, v0
	v_lshlrev_b32_e32 v170, 16, v2
	v_and_b32_e32 v171, 0xffff0000, v2
	v_lshlrev_b32_e32 v180, 16, v3
	v_and_b32_e32 v181, 0xffff0000, v3
	v_lshl_add_u32 v174, v136, 3, s8
	s_cselect_b64 s[8:9], -1, 0
	s_cmp_eq_u32 s15, 3
	v_pk_mul_f32 v[182:183], v[92:93], v[138:139]
	v_pk_mul_f32 v[184:185], v[88:89], v[170:171]
	v_pk_mul_f32 v[186:187], v[90:91], v[180:181]
	v_pk_fma_f32 v[92:93], v[92:93], v[138:139], v[168:169]
	v_pk_fma_f32 v[88:89], v[88:89], v[170:171], v[166:167]
	v_pk_fma_f32 v[90:91], v[90:91], v[180:181], v[162:163]
	s_cselect_b64 s[22:23], -1, 0
	s_cmp_lg_u32 s15, 3
	v_cndmask_b32_e64 v171, v95, v179, s[8:9]
	v_cndmask_b32_e64 v170, v94, v178, s[8:9]
	v_cndmask_b32_e64 v169, v93, v183, s[8:9]
	v_cndmask_b32_e64 v168, v92, v182, s[8:9]
	v_cndmask_b32_e64 v163, v91, v187, s[8:9]
	v_cndmask_b32_e64 v162, v90, v186, s[8:9]
	v_cndmask_b32_e64 v167, v89, v185, s[8:9]
	v_cndmask_b32_e64 v166, v88, v184, s[8:9]
	v_lshlrev_b32_e32 v88, 1, v174
	s_cbranch_scc1 .LBB0_926
	v_cvt_pk_bf16_f32 v90, v168, v169
	v_cvt_pk_bf16_f32 v91, v170, v171
	v_cvt_pk_bf16_f32 v92, v166, v167
	v_cvt_pk_bf16_f32 v93, v162, v163
	v_lshl_add_u32 v89, v172, 11, v88
	buffer_store_dwordx4 v[90:93], v89, s[84:87], 0 offen sc1
